# MFMA fold + 13 s_nop pad so code after the prologue keeps its baseline 256B phase
# speedup vs baseline: 1.0046x; 1.0046x over previous
; __device__ __forceinline__ unsigned f2bf(float f) { return pg8::cvt_pk_bf16(f, 0.f) & 0xffffu; }
; __device__ __forceinline__ void prologue(const Params& p, LAS unsigned char* lds, int gw, int ngw, int wave, int lane) {
;     ...
;     {
;         const float* pw = p.in[I_ABPW]; const float* ps = p.in[I_ABPS]; const float* wo = p.in[I_ABWOUT] + (size_t)512 * 1024;
;         bf16* WT = (bf16*)(ws + W_WOUT);
;         const int gt = gw * 64 + lane, ngt = ngw * 64;
;         for (int o = gt; o < 128 * 1024; o += ngt) {
;             const int n = o & 1023, d = o >> 10;
;             float a[4] = {0.f, 0.f, 0.f, 0.f};
; #pragma unroll 4
;             for (int e = 0; e < 128; ++e) {
; #pragma unroll
;                 for (int g = 0; g < 4; ++g) a[g] += pw[((size_t)g * 128 + d) * 128 + e] * ps[g * 128 + e] * wo[((size_t)g * 128 + e) * 1024 + n]; }
; #pragma unroll
;             for (int g = 0; g < 4; ++g) WT[(size_t)n * 1024 + 512 + g * 128 + d] = (bf16)f2bf(a[g]); }
;     }
.Lfold_done:
	s_nop 0
	s_nop 0
	s_nop 0
	s_nop 0
	s_nop 0
	s_nop 0
	s_nop 0
	s_nop 0
	s_nop 0
	s_nop 0
	s_nop 0
	s_nop 0
	s_nop 0
